# v20 with the held V tile's LDS writes issued behind the first four K-fragment reads of the half-step
# baseline (speedup 1.0000x reference)
; __device__ __forceinline__ void finishSM(f32x16& p0, f32x16& p1, float alpha, float& l_reg, bf16x8& pa0, bf16x8& pa1, bf16x8& pa2, bf16x8& pa3) {
;     for (int r = 0; r < 16; ++r) p1[r] = __builtin_amdgcn_exp2f(p1[r]);
;     float ps = 0; for (int r = 0; r < 16; ++r) ps += p0[r]; for (int r = 0; r < 16; ++r) ps += p1[r];
;     { auto rr = __builtin_amdgcn_permlane32_swap(__float_as_uint(ps), __float_as_uint(ps), false, false);
;       ps = __uint_as_float(rr[0]) + __uint_as_float(rr[1]); }
;     l_reg = l_reg * alpha + ps;
;     ...
;     PK4(p0, 0, pa0); PK4(p0, 8, pa1); PK4(p1, 0, pa2); PK4(p1, 8, pa3);
;     ...
; }
; template <int KB>
; __device__ __forceinline__ void qkt(f32x16& p0, f32x16& p1, const char* K_lds, int r32, int hi, const bf16x8* qr) {
;     p0 = f32x16{}; p1 = f32x16{};
;     const char* kb[4];
; #pragma unroll
;     for (int dd = 0; dd < 4; ++dd) kb[dd] = K_lds + KB * SHM_K + KSWZ(r32, (dd * 16 + hi * 8) * 2);
; #pragma unroll
;     for (int d0 = 0; d0 < 8; ++d0) { const char* a = kb[d0 & 3] + (d0 >> 2) * 128;
;         bf16x8 b0 = *reinterpret_cast<const bf16x8*>(a);
;         bf16x8 b1 = *reinterpret_cast<const bf16x8*>(a + 32 * 256);
;         p0 = __builtin_amdgcn_mfma_f32_32x32x16_bf16(b0, qr[d0], p0, 0, 0, 0);
;         p1 = __builtin_amdgcn_mfma_f32_32x32x16_bf16(b1, qr[d0], p1, 0, 0, 0); }
.LBB0_89:
	s_waitcnt vmcnt(0)
	ds_read_b128 v[66:69], v169 offset:49152
	ds_read_b128 v[70:73], v169 offset:57344
	ds_read_b128 v[100:103], v193 offset:49152
	ds_read_b128 v[136:139], v193 offset:57344
	s_cmp_eq_u32 s100, 0
	s_cbranch_scc1 .Lmy_hs1_nov
	ds_write_b128 v191, v[242:245] offset:16384
	ds_write_b128 v192, v[246:249] offset:16384
.Lmy_hs1_nov:
	s_mov_b32 s100, 0
	s_waitcnt lgkmcnt(3)
	v_mfma_f32_32x32x16_bf16 v[82:97], v[66:69], v[132:135], 0
	v_add_f32_e32 v148, 0, v231
	v_add_f32_e32 v148, v233, v148
	v_add_f32_e32 v148, v229, v148
	v_add_f32_e32 v148, v232, v148
	v_add_f32_e32 v148, v228, v148
	s_waitcnt lgkmcnt(2)
	v_mfma_f32_32x32x16_bf16 v[66:81], v[70:73], v[132:135], 0
	v_add_f32_e32 v148, v230, v148
	v_add_f32_e32 v148, v226, v148
	v_add_f32_e32 v148, v227, v148
	v_add_f32_e32 v148, v223, v148
	v_add_f32_e32 v148, v225, v148
	s_waitcnt lgkmcnt(1)
	v_mfma_f32_32x32x16_bf16 v[82:97], v[100:103], v[128:131], v[82:97]
	v_add_f32_e32 v148, v209, v148
	v_add_f32_e32 v148, v224, v148
	v_add_f32_e32 v148, v206, v148
	v_add_f32_e32 v148, v208, v148
	v_add_f32_e32 v148, v205, v148
	s_waitcnt lgkmcnt(0)
	v_mfma_f32_32x32x16_bf16 v[66:81], v[136:139], v[128:131], v[66:81]
	v_add_f32_e32 v148, v207, v148
	v_exp_f32_e32 v140, v152
	v_exp_f32_e32 v141, v153
	v_exp_f32_e32 v142, v180
	v_exp_f32_e32 v143, v181
	ds_read_b128 v[100:103], v194 offset:49152
	ds_read_b128 v[136:139], v194 offset:57344
	s_waitcnt lgkmcnt(1)
	v_mfma_f32_32x32x16_bf16 v[82:97], v[100:103], v[124:127], v[82:97]
	v_exp_f32_e32 v144, v160
	v_exp_f32_e32 v145, v161
	v_exp_f32_e32 v146, v154
	v_exp_f32_e32 v147, v155
	v_exp_f32_e32 v178, v178
	s_waitcnt lgkmcnt(0)
	v_mfma_f32_32x32x16_bf16 v[66:81], v[136:139], v[124:127], v[66:81]
	v_exp_f32_e32 v179, v179
	v_exp_f32_e32 v162, v162
	v_exp_f32_e32 v163, v163
	v_add_f32_e32 v148, v178, v148
	v_add_f32_e32 v148, v179, v148
	ds_read_b128 v[100:103], v195 offset:49152
	ds_read_b128 v[136:139], v195 offset:57344
	s_waitcnt lgkmcnt(1)
	v_mfma_f32_32x32x16_bf16 v[82:97], v[100:103], v[120:123], v[82:97]
	v_add_f32_e32 v148, v162, v148
	v_exp_f32_e32 v158, v158
	v_exp_f32_e32 v159, v159
	v_exp_f32_e32 v156, v156
	v_exp_f32_e32 v157, v157
	s_waitcnt lgkmcnt(0)
	v_mfma_f32_32x32x16_bf16 v[66:81], v[136:139], v[120:123], v[66:81]
	v_add_f32_e32 v148, v163, v148
	v_add_f32_e32 v148, v158, v148
	v_add_f32_e32 v148, v159, v148
	v_add_f32_e32 v148, v156, v148
	v_add_f32_e32 v148, v157, v148
	ds_read_b128 v[100:103], v169 offset:49280
	ds_read_b128 v[136:139], v169 offset:57472
	s_waitcnt lgkmcnt(1)
	v_mfma_f32_32x32x16_bf16 v[82:97], v[100:103], v[116:119], v[82:97]
	v_add_f32_e32 v148, v140, v148
	v_add_f32_e32 v148, v141, v148
	v_add_f32_e32 v148, v142, v148
	v_add_f32_e32 v148, v143, v148
	v_add_f32_e32 v148, v144, v148
	s_waitcnt lgkmcnt(0)
	v_mfma_f32_32x32x16_bf16 v[66:81], v[136:139], v[116:119], v[66:81]
	v_add_f32_e32 v148, v145, v148
	v_add_f32_e32 v148, v146, v148
	v_add_f32_e32 v199, v147, v148
	v_mov_b32_e32 v200, v199
	s_nop 1
	v_permlane32_swap_b32_e32 v199, v200
	v_cvt_pk_bf16_f32 v148, v231, v233
	ds_read_b128 v[100:103], v193 offset:49280
	ds_read_b128 v[136:139], v193 offset:57472
	s_waitcnt lgkmcnt(1)
	v_mfma_f32_32x32x16_bf16 v[82:97], v[100:103], v[112:115], v[82:97]
	v_cvt_pk_bf16_f32 v149, v229, v232
	v_cvt_pk_bf16_f32 v150, v228, v230
	v_cvt_pk_bf16_f32 v151, v226, v227
	v_cvt_pk_bf16_f32 v152, v223, v225
	v_cvt_pk_bf16_f32 v153, v209, v224
	s_waitcnt lgkmcnt(0)
	v_mfma_f32_32x32x16_bf16 v[66:81], v[136:139], v[112:115], v[66:81]
	v_cvt_pk_bf16_f32 v154, v206, v208
	v_cvt_pk_bf16_f32 v155, v205, v207
	v_cvt_pk_bf16_f32 v158, v158, v159
	v_cvt_pk_bf16_f32 v159, v156, v157
	v_cvt_pk_bf16_f32 v156, v178, v179
	ds_read_b128 v[100:103], v194 offset:49280
	ds_read_b128 v[136:139], v194 offset:57472
	s_waitcnt lgkmcnt(1)
	v_mfma_f32_32x32x16_bf16 v[82:97], v[100:103], v[108:111], v[82:97]
	v_cvt_pk_bf16_f32 v157, v162, v163
	v_cvt_pk_bf16_f32 v160, v140, v141
	v_cvt_pk_bf16_f32 v161, v142, v143
	v_cvt_pk_bf16_f32 v162, v144, v145
	v_cvt_pk_bf16_f32 v163, v146, v147
	s_waitcnt lgkmcnt(0)
	v_mfma_f32_32x32x16_bf16 v[66:81], v[136:139], v[108:111], v[66:81]
	s_nop 0
	v_permlane32_swap_b32_e32 v148, v150
	v_permlane32_swap_b32_e32 v149, v151
	v_permlane32_swap_b32_e32 v152, v154
	v_permlane32_swap_b32_e32 v153, v155
	ds_read_b128 v[100:103], v195 offset:49280
	ds_read_b128 v[136:139], v195 offset:57472
	s_waitcnt lgkmcnt(1)
	v_mfma_f32_32x32x16_bf16 v[82:97], v[100:103], v[104:107], v[82:97]
	v_permlane32_swap_b32_e32 v156, v158
	v_permlane32_swap_b32_e32 v157, v159
	v_permlane32_swap_b32_e32 v160, v162
	v_permlane32_swap_b32_e32 v161, v163
	s_waitcnt lgkmcnt(0)
	v_mfma_f32_32x32x16_bf16 v[66:81], v[136:139], v[104:107], v[66:81]
	v_add_u32_e32 v178, s7, v166
	v_add_u32_e32 v100, 1, v178
	v_add_u32_e32 v102, 33, v178
	v_ashrrev_i32_e32 v101, 31, v100
	v_ashrrev_i32_e32 v103, 31, v102
	v_lshlrev_b64 v[140:141], 8, v[100:101]
	v_lshlrev_b64 v[142:143], 8, v[102:103]
	v_lshl_add_u64 v[100:101], v[170:171], 0, v[140:141]
	v_lshl_add_u64 v[136:137], v[170:171], 0, v[142:143]
	v_lshl_add_u64 v[140:141], v[176:177], 0, v[140:141]
	v_lshl_add_u64 v[144:145], v[176:177], 0, v[142:143]
	global_load_dwordx4 v[100:103], v[100:101], off
	s_nop 0
	global_load_dwordx4 v[136:139], v[136:137], off
	s_nop 0
	global_load_dwordx4 v[140:143], v[140:141], off
	s_nop 0
	global_load_dwordx4 v[144:147], v[144:145], off
	ds_read_b64_tr_b16 v[172:173], v185 offset:0
	ds_read_b64_tr_b16 v[174:175], v185 offset:0x800
	ds_read_b64_tr_b16 v[202:203], v185 offset:0x1000
	ds_read_b64_tr_b16 v[204:205], v185 offset:0x1800
	ds_read_b64_tr_b16 v[206:207], v185 offset:0x2000
	ds_read_b64_tr_b16 v[208:209], v185 offset:0x2800
	ds_read_b64_tr_b16 v[224:225], v185 offset:0x3000
	ds_read_b64_tr_b16 v[226:227], v185 offset:0x3800
	s_waitcnt lgkmcnt(0)
; __device__ __forceinline__ void mask_tile(f32x16& p0, f32x16& p1, int dq, unsigned W) {
;     const float NEG = -__builtin_inff();
; #pragma unroll
;     for (int r = 0; r < 16; ++r) {
;         const int c = (r & 3) + 8 * (r >> 2);
;         if ((unsigned)(dq - c) >= W) p0[r] = NEG;
;         if ((unsigned)(dq - c - 32) >= W) p1[r] = NEG;
;     }
; }
; template <int VB>
; __device__ __forceinline__ void pv_tile(f32x16* o, int vb0, bf16x8 pa0, bf16x8 pa1, bf16x8 pa2, bf16x8 pa3) {
;     ...
;     PV_D0(0); PV_D0(1); PV_D0(2); PV_D0(3);
	s_nop 0
	v_mfma_f32_32x32x16_bf16 v[50:65], v[148:151], v[172:175], v[50:65]
	ds_read_b64_tr_b16 v[172:173], v185 offset:0x200
	ds_read_b64_tr_b16 v[174:175], v185 offset:0xa00
	v_mfma_f32_32x32x16_bf16 v[50:65], v[152:155], v[202:205], v[50:65]
	ds_read_b64_tr_b16 v[202:203], v185 offset:0x1200
	ds_read_b64_tr_b16 v[204:205], v185 offset:0x1a00
	v_mfma_f32_32x32x16_bf16 v[50:65], v[156:159], v[206:209], v[50:65]
	ds_read_b64_tr_b16 v[206:207], v185 offset:0x2200
	ds_read_b64_tr_b16 v[208:209], v185 offset:0x2a00
	v_mfma_f32_32x32x16_bf16 v[50:65], v[160:163], v[224:227], v[50:65]
	ds_read_b64_tr_b16 v[224:225], v185 offset:0x3200
	ds_read_b64_tr_b16 v[226:227], v185 offset:0x3a00
	s_waitcnt lgkmcnt(0)
	v_mfma_f32_32x32x16_bf16 v[34:49], v[148:151], v[172:175], v[34:49]
	ds_read_b64_tr_b16 v[172:173], v185 offset:0x400
	ds_read_b64_tr_b16 v[174:175], v185 offset:0xc00
	v_mfma_f32_32x32x16_bf16 v[34:49], v[152:155], v[202:205], v[34:49]
	ds_read_b64_tr_b16 v[202:203], v185 offset:0x1400
	ds_read_b64_tr_b16 v[204:205], v185 offset:0x1c00
	v_mfma_f32_32x32x16_bf16 v[34:49], v[156:159], v[206:209], v[34:49]
	ds_read_b64_tr_b16 v[206:207], v185 offset:0x2400
	ds_read_b64_tr_b16 v[208:209], v185 offset:0x2c00
	v_mfma_f32_32x32x16_bf16 v[34:49], v[160:163], v[224:227], v[34:49]
	ds_read_b64_tr_b16 v[224:225], v185 offset:0x3400
	ds_read_b64_tr_b16 v[226:227], v185 offset:0x3c00
	s_waitcnt lgkmcnt(0)
	v_mfma_f32_32x32x16_bf16 v[18:33], v[148:151], v[172:175], v[18:33]
	ds_read_b64_tr_b16 v[172:173], v185 offset:0x600
	ds_read_b64_tr_b16 v[174:175], v185 offset:0xe00
	v_mfma_f32_32x32x16_bf16 v[18:33], v[152:155], v[202:205], v[18:33]
	ds_read_b64_tr_b16 v[202:203], v185 offset:0x1600
	ds_read_b64_tr_b16 v[204:205], v185 offset:0x1e00
	v_mfma_f32_32x32x16_bf16 v[18:33], v[156:159], v[206:209], v[18:33]
	ds_read_b64_tr_b16 v[206:207], v185 offset:0x2600
	ds_read_b64_tr_b16 v[208:209], v185 offset:0x2e00
	v_mfma_f32_32x32x16_bf16 v[18:33], v[160:163], v[224:227], v[18:33]
	ds_read_b64_tr_b16 v[224:225], v185 offset:0x3600
	ds_read_b64_tr_b16 v[226:227], v185 offset:0x3e00
	s_waitcnt lgkmcnt(0)
	v_mfma_f32_32x32x16_bf16 v[2:17], v[148:151], v[172:175], v[2:17]
	s_cmp_le_i32 s7, s6
	v_mfma_f32_32x32x16_bf16 v[2:17], v[152:155], v[202:205], v[2:17]
	v_mfma_f32_32x32x16_bf16 v[2:17], v[156:159], v[206:209], v[2:17]
	v_mfma_f32_32x32x16_bf16 v[2:17], v[160:163], v[224:227], v[2:17]
	s_cbranch_scc1 .LBB0_91
	v_add_u32_e32 v148, 0x4000007b, v197
	v_cmp_gt_u32_e32 vcc, 2.0, v148
	v_add_u32_e32 v148, 0x5b, v197
	s_nop 0
	v_cndmask_b32_e32 v82, v220, v82, vcc
	v_cmp_lt_u32_e32 vcc, s33, v148
	v_add_u32_e32 v148, 0x7a, v197
	s_nop 0
	v_cndmask_b32_e32 v66, v220, v66, vcc
	v_cmp_lt_u32_e32 vcc, s33, v148
	v_add_u32_e32 v148, 0x5a, v197
	s_nop 0
	v_cndmask_b32_e32 v83, v220, v83, vcc
	v_cmp_lt_u32_e32 vcc, s33, v148
	v_add_u32_e32 v148, 0x79, v197
	s_nop 0
	v_cndmask_b32_e32 v67, v220, v67, vcc
	v_cmp_lt_u32_e32 vcc, s33, v148
	v_add_u32_e32 v148, 0x59, v197
	s_nop 0
	v_cndmask_b32_e32 v84, v220, v84, vcc
	v_cmp_lt_u32_e32 vcc, s33, v148
	v_add_u32_e32 v148, 0x78, v197
	s_nop 0
	v_cndmask_b32_e32 v68, v220, v68, vcc
	v_cmp_lt_u32_e32 vcc, s33, v148
	v_add_u32_e32 v148, 0x58, v197
	s_nop 0
	v_cndmask_b32_e32 v85, v220, v85, vcc
	v_cmp_lt_u32_e32 vcc, s33, v148
	v_add_u32_e32 v148, 0x73, v197
	s_nop 0
	v_cndmask_b32_e32 v69, v220, v69, vcc
	v_cmp_lt_u32_e32 vcc, s33, v148
	v_add_u32_e32 v148, 0x53, v197
	s_nop 0
	v_cndmask_b32_e32 v86, v220, v86, vcc
	v_cmp_lt_u32_e32 vcc, s33, v148
	v_add_u32_e32 v148, 0x72, v197
	s_nop 0
	v_cndmask_b32_e32 v70, v220, v70, vcc
	v_cmp_lt_u32_e32 vcc, s33, v148
	v_add_u32_e32 v148, 0x52, v197
	s_nop 0
	v_cndmask_b32_e32 v87, v220, v87, vcc
	v_cmp_lt_u32_e32 vcc, s33, v148
	v_add_u32_e32 v148, 0x71, v197
	s_nop 0
	v_cndmask_b32_e32 v71, v220, v71, vcc
	v_cmp_lt_u32_e32 vcc, s33, v148
	v_add_u32_e32 v148, 0x51, v197
	s_nop 0
	v_cndmask_b32_e32 v88, v220, v88, vcc
	v_cmp_lt_u32_e32 vcc, s33, v148
	v_add_u32_e32 v148, 0x70, v197
	s_nop 0
	v_cndmask_b32_e32 v72, v220, v72, vcc
	v_cmp_lt_u32_e32 vcc, s33, v148
	v_add_u32_e32 v148, 0x50, v197
	s_nop 0
	v_cndmask_b32_e32 v89, v220, v89, vcc
	v_cmp_lt_u32_e32 vcc, s33, v148
	v_add_u32_e32 v148, 0x6b, v197
	s_nop 0
	v_cndmask_b32_e32 v73, v220, v73, vcc
	v_cmp_lt_u32_e32 vcc, s33, v148
	v_add_u32_e32 v148, 0x4b, v197
	s_nop 0
	v_cndmask_b32_e32 v90, v220, v90, vcc
	v_cmp_lt_u32_e32 vcc, s33, v148
	v_add_u32_e32 v148, 0x6a, v197
	s_nop 0
	v_cndmask_b32_e32 v74, v220, v74, vcc
	v_cmp_lt_u32_e32 vcc, s33, v148
	v_add_u32_e32 v148, 0x4a, v197
	s_nop 0
	v_cndmask_b32_e32 v91, v220, v91, vcc
	v_cmp_lt_u32_e32 vcc, s33, v148
	v_add_u32_e32 v148, 0x69, v197
	s_nop 0
	v_cndmask_b32_e32 v75, v220, v75, vcc
	v_cmp_lt_u32_e32 vcc, s33, v148
	v_add_u32_e32 v148, 0x49, v197
	s_nop 0
	v_cndmask_b32_e32 v92, v220, v92, vcc
	v_cmp_lt_u32_e32 vcc, s33, v148
	v_add_u32_e32 v148, 0x68, v197
	s_nop 0
	v_cndmask_b32_e32 v76, v220, v76, vcc
	v_cmp_lt_u32_e32 vcc, s33, v148
	v_add_u32_e32 v148, 0x48, v197
	s_nop 0
	v_cndmask_b32_e32 v93, v220, v93, vcc
	v_cmp_lt_u32_e32 vcc, s33, v148
	v_add_u32_e32 v148, 0x63, v197
	s_nop 0
	v_cndmask_b32_e32 v77, v220, v77, vcc
	v_cmp_lt_u32_e32 vcc, s33, v148
	v_add_u32_e32 v148, 0x43, v197
	s_nop 0
	v_cndmask_b32_e32 v94, v220, v94, vcc
	v_cmp_lt_u32_e32 vcc, s33, v148
	v_add_u32_e32 v148, 0x62, v197
	s_nop 0
	v_cndmask_b32_e32 v78, v220, v78, vcc
	v_cmp_lt_u32_e32 vcc, s33, v148
	v_add_u32_e32 v148, 0x42, v197
	s_nop 0
	v_cndmask_b32_e32 v95, v220, v95, vcc
	v_cmp_lt_u32_e32 vcc, s33, v148
	v_add_u32_e32 v148, 0x61, v197
	s_nop 0
	v_cndmask_b32_e32 v79, v220, v79, vcc
	v_cmp_lt_u32_e32 vcc, s33, v148
	v_add_u32_e32 v148, 0x41, v197
	s_nop 0
	v_cndmask_b32_e32 v96, v220, v96, vcc
	v_cmp_lt_u32_e32 vcc, s33, v148
	v_add_u32_e32 v148, 0x60, v197
	s_nop 0
	v_cndmask_b32_e32 v80, v220, v80, vcc
	v_cmp_lt_u32_e32 vcc, s33, v148
	v_add_u32_e32 v148, 64, v197
	s_nop 0
	v_cndmask_b32_e32 v97, v220, v97, vcc
	v_cmp_lt_u32_e32 vcc, s33, v148
	s_nop 1
	v_cndmask_b32_e32 v81, v220, v81, vcc

; __device__ __forceinline__ void partialSM(f32x16& p0, f32x16& p1, float& m_reg, float& mn, float& alpha, bool rs) {
;     ...
;     constexpr float C2 = 1.4426950408889634f * SCALE;
;     if (__builtin_expect(__all((pmax - m_reg) * SCALE <= THR), 1)) { mn = m_reg; alpha = 1.f; }
;     else { mn = fmaxf(m_reg, pmax); alpha = __builtin_amdgcn_exp2f((m_reg - mn) * C2); m_reg = mn; }
;     const float mnL = rs ? -mn * C2 : -__builtin_inff();
;     for (int r = 0; r < 16; ++r) p0[r] = fmaf(p0[r], C2, mnL); for (int r = 0; r < 16; ++r) p1[r] = fmaf(p1[r], C2, mnL);
;     for (int r = 0; r < 16; ++r) p0[r] = __builtin_amdgcn_exp2f(p0[r]);
.LBB0_95:
	v_cndmask_b32_e64 v179, v148, v198, s[42:43]
	v_mul_f32_e32 v148, 0xbe0293ee, v179
	v_cndmask_b32_e64 v180, v220, v148, s[40:41]
	v_fmamk_f32 v82, v82, 0x3e0293ee, v180
	v_fmamk_f32 v83, v83, 0x3e0293ee, v180
	v_fmamk_f32 v84, v84, 0x3e0293ee, v180
	v_fmamk_f32 v85, v85, 0x3e0293ee, v180
	v_fmamk_f32 v86, v86, 0x3e0293ee, v180
	v_fmamk_f32 v87, v87, 0x3e0293ee, v180
	v_fmamk_f32 v88, v88, 0x3e0293ee, v180
	v_fmamk_f32 v89, v89, 0x3e0293ee, v180
	v_fmamk_f32 v90, v90, 0x3e0293ee, v180
	v_fmamk_f32 v91, v91, 0x3e0293ee, v180
	v_fmamk_f32 v92, v92, 0x3e0293ee, v180
	v_fmamk_f32 v93, v93, 0x3e0293ee, v180
	v_fmamk_f32 v94, v94, 0x3e0293ee, v180
	v_fmamk_f32 v95, v95, 0x3e0293ee, v180
	v_fmamk_f32 v96, v96, 0x3e0293ee, v180
	v_fmamk_f32 v97, v97, 0x3e0293ee, v180
	v_exp_f32_e32 v148, v82
	v_exp_f32_e32 v163, v83
	v_exp_f32_e32 v149, v84
	v_exp_f32_e32 v162, v85
	v_exp_f32_e32 v150, v86
	v_exp_f32_e32 v161, v87
	v_exp_f32_e32 v151, v88
	v_exp_f32_e32 v160, v89
	v_exp_f32_e32 v152, v90
	v_exp_f32_e32 v159, v91
	v_exp_f32_e32 v153, v92
	v_exp_f32_e32 v158, v93
	v_exp_f32_e32 v154, v94
	v_exp_f32_e32 v157, v95
	v_exp_f32_e32 v155, v96
	v_exp_f32_e32 v156, v97
	v_fmamk_f32 v203, v73, 0x3e0293ee, v180
	v_fmamk_f32 v204, v74, 0x3e0293ee, v180
	v_fmamk_f32 v208, v66, 0x3e0293ee, v180
	v_fmamk_f32 v209, v67, 0x3e0293ee, v180
	v_fmamk_f32 v223, v68, 0x3e0293ee, v180
	v_fmamk_f32 v224, v69, 0x3e0293ee, v180
	v_fmamk_f32 v225, v70, 0x3e0293ee, v180
	v_fmamk_f32 v198, v71, 0x3e0293ee, v180
	v_fmamk_f32 v201, v72, 0x3e0293ee, v180
	v_fmamk_f32 v205, v75, 0x3e0293ee, v180
	v_fmamk_f32 v206, v76, 0x3e0293ee, v180
	v_fmamk_f32 v207, v77, 0x3e0293ee, v180
	v_fmamk_f32 v181, v78, 0x3e0293ee, v180
	v_fmamk_f32 v226, v79, 0x3e0293ee, v180
	v_fmamk_f32 v227, v80, 0x3e0293ee, v180
	v_fmac_f32_e32 v180, 0x3e0293ee, v81
	s_waitcnt lgkmcnt(0)
	s_barrier
; __device__ __forceinline__ void finishSM(f32x16& p0, f32x16& p1, float alpha, float& l_reg, bf16x8& pa0, bf16x8& pa1, bf16x8& pa2, bf16x8& pa3) {
;     for (int r = 0; r < 16; ++r) p1[r] = __builtin_amdgcn_exp2f(p1[r]);
;     float ps = 0; for (int r = 0; r < 16; ++r) ps += p0[r]; for (int r = 0; r < 16; ++r) ps += p1[r];
;     { auto rr = __builtin_amdgcn_permlane32_swap(__float_as_uint(ps), __float_as_uint(ps), false, false);
;       ps = __uint_as_float(rr[0]) + __uint_as_float(rr[1]); }
;     l_reg = l_reg * alpha + ps;
;     ...
;     PK4(p0, 0, pa0); PK4(p0, 8, pa1); PK4(p1, 0, pa2); PK4(p1, 8, pa3);
;     ...
; }
; template <int KB>
; __device__ __forceinline__ void qkt(f32x16& p0, f32x16& p1, const char* K_lds, int r32, int hi, const bf16x8* qr) {
;     p0 = f32x16{}; p1 = f32x16{};
;     const char* kb[4];
; #pragma unroll
;     for (int dd = 0; dd < 4; ++dd) kb[dd] = K_lds + KB * SHM_K + KSWZ(r32, (dd * 16 + hi * 8) * 2);
; #pragma unroll
;     for (int d0 = 0; d0 < 8; ++d0) { const char* a = kb[d0 & 3] + (d0 >> 2) * 128;
;         bf16x8 b0 = *reinterpret_cast<const bf16x8*>(a);
;         bf16x8 b1 = *reinterpret_cast<const bf16x8*>(a + 32 * 256);
;         p0 = __builtin_amdgcn_mfma_f32_32x32x16_bf16(b0, qr[d0], p0, 0, 0, 0);
;         p1 = __builtin_amdgcn_mfma_f32_32x32x16_bf16(b1, qr[d0], p1, 0, 0, 0); }
	s_waitcnt vmcnt(0)
	ds_read_b128 v[66:69], v169 offset:32768
	ds_read_b128 v[70:73], v169 offset:40960
	ds_read_b128 v[172:175], v193 offset:32768
	ds_read_b128 v[228:231], v193 offset:40960
	ds_write_b128 v191, v[100:103]
	ds_write_b128 v192, v[136:139]
	s_waitcnt lgkmcnt(3)
	v_mfma_f32_32x32x16_bf16 v[82:97], v[66:69], v[132:135], 0
	v_exp_f32_e32 v198, v198
	v_exp_f32_e32 v201, v201
	v_exp_f32_e32 v214, v204
	v_exp_f32_e32 v205, v205
	v_exp_f32_e32 v206, v206
	s_waitcnt lgkmcnt(2)
	v_mfma_f32_32x32x16_bf16 v[66:81], v[70:73], v[132:135], 0
	v_exp_f32_e32 v207, v207
	v_exp_f32_e32 v181, v181
	v_exp_f32_e32 v215, v226
	v_exp_f32_e32 v216, v227
	v_exp_f32_e32 v180, v180
	s_waitcnt lgkmcnt(1)
	v_mfma_f32_32x32x16_bf16 v[82:97], v[172:175], v[128:131], v[82:97]
	v_exp_f32_e32 v218, v209
	v_exp_f32_e32 v209, v203
	v_add_f32_e32 v203, 0, v148
	v_add_f32_e32 v203, v163, v203
	v_add_f32_e32 v203, v149, v203
	s_waitcnt lgkmcnt(0)
	v_mfma_f32_32x32x16_bf16 v[66:81], v[228:231], v[128:131], v[66:81]
	v_add_f32_e32 v203, v162, v203
	v_add_f32_e32 v203, v150, v203
	v_add_f32_e32 v203, v161, v203
	v_add_f32_e32 v203, v151, v203
	v_add_f32_e32 v203, v160, v203
	ds_read_b128 v[172:175], v194 offset:32768
	ds_read_b128 v[228:231], v194 offset:40960
	s_waitcnt lgkmcnt(1)
	v_mfma_f32_32x32x16_bf16 v[82:97], v[172:175], v[124:127], v[82:97]
	v_add_f32_e32 v203, v152, v203
	v_add_f32_e32 v203, v159, v203
	v_add_f32_e32 v203, v153, v203
	v_add_f32_e32 v203, v158, v203
	v_exp_f32_e32 v217, v208
	s_waitcnt lgkmcnt(0)
	v_mfma_f32_32x32x16_bf16 v[66:81], v[228:231], v[124:127], v[66:81]
	v_add_f32_e32 v203, v154, v203
	v_add_f32_e32 v203, v157, v203
	v_exp_f32_e32 v219, v223
	v_add_f32_e32 v203, v155, v203
	v_exp_f32_e32 v222, v224
	ds_read_b128 v[172:175], v195 offset:32768
	ds_read_b128 v[228:231], v195 offset:40960
	s_waitcnt lgkmcnt(1)
	v_mfma_f32_32x32x16_bf16 v[82:97], v[172:175], v[120:123], v[82:97]
	v_add_f32_e32 v203, v156, v203
	v_exp_f32_e32 v208, v225
	v_add_f32_e32 v203, v217, v203
	v_add_f32_e32 v203, v218, v203
	v_add_f32_e32 v203, v219, v203
	s_waitcnt lgkmcnt(0)
	v_mfma_f32_32x32x16_bf16 v[66:81], v[228:231], v[120:123], v[66:81]
	v_add_f32_e32 v203, v222, v203
	v_add_f32_e32 v203, v208, v203
	v_add_f32_e32 v203, v198, v203
	v_add_f32_e32 v203, v201, v203
	v_add_f32_e32 v203, v209, v203
	ds_read_b128 v[172:175], v169 offset:32896
	ds_read_b128 v[228:231], v169 offset:41088
	s_waitcnt lgkmcnt(1)
	v_mfma_f32_32x32x16_bf16 v[82:97], v[172:175], v[116:119], v[82:97]
	v_add_f32_e32 v203, v214, v203
	v_add_f32_e32 v203, v205, v203
	v_add_f32_e32 v203, v206, v203
	v_add_f32_e32 v203, v207, v203
	v_add_f32_e32 v203, v181, v203
	s_waitcnt lgkmcnt(0)
	v_mfma_f32_32x32x16_bf16 v[66:81], v[228:231], v[116:119], v[66:81]
	v_add_f32_e32 v203, v215, v203
	v_add_f32_e32 v203, v216, v203
	v_add_f32_e32 v203, v180, v203
	v_mov_b32_e32 v204, v203
	v_cvt_pk_bf16_f32 v148, v148, v163
	ds_read_b128 v[172:175], v193 offset:32896
	ds_read_b128 v[228:231], v193 offset:41088
	s_waitcnt lgkmcnt(1)
	v_mfma_f32_32x32x16_bf16 v[82:97], v[172:175], v[112:115], v[82:97]
	v_cvt_pk_bf16_f32 v149, v149, v162
	v_cvt_pk_bf16_f32 v150, v150, v161
	v_cvt_pk_bf16_f32 v151, v151, v160
	v_cvt_pk_bf16_f32 v152, v152, v159
	v_cvt_pk_bf16_f32 v153, v153, v158
	s_waitcnt lgkmcnt(0)
	v_mfma_f32_32x32x16_bf16 v[66:81], v[228:231], v[112:115], v[66:81]
	v_cvt_pk_bf16_f32 v154, v154, v157
	v_cvt_pk_bf16_f32 v155, v155, v156
	v_cvt_pk_bf16_f32 v156, v217, v218
	v_cvt_pk_bf16_f32 v157, v219, v222
	v_cvt_pk_bf16_f32 v158, v208, v198
	ds_read_b128 v[172:175], v194 offset:32896
	ds_read_b128 v[228:231], v194 offset:41088
	s_waitcnt lgkmcnt(1)
	v_mfma_f32_32x32x16_bf16 v[82:97], v[172:175], v[108:111], v[82:97]
	v_cvt_pk_bf16_f32 v159, v201, v209
	v_cvt_pk_bf16_f32 v160, v214, v205
	v_cvt_pk_bf16_f32 v161, v206, v207
	v_cvt_pk_bf16_f32 v162, v181, v215
	v_cvt_pk_bf16_f32 v163, v216, v180
	s_waitcnt lgkmcnt(0)
	v_mfma_f32_32x32x16_bf16 v[66:81], v[228:231], v[108:111], v[66:81]
	s_nop 1
	v_permlane32_swap_b32_e32 v203, v204
	v_permlane32_swap_b32_e32 v148, v150
	v_permlane32_swap_b32_e32 v149, v151
	v_permlane32_swap_b32_e32 v152, v154
	v_permlane32_swap_b32_e32 v153, v155
	ds_read_b128 v[172:175], v195 offset:32896
	ds_read_b128 v[228:231], v195 offset:41088
	s_waitcnt lgkmcnt(1)
	v_mfma_f32_32x32x16_bf16 v[82:97], v[172:175], v[104:107], v[82:97]
	v_permlane32_swap_b32_e32 v156, v158
	v_permlane32_swap_b32_e32 v157, v159
	v_permlane32_swap_b32_e32 v160, v162
	v_permlane32_swap_b32_e32 v161, v163
	s_waitcnt lgkmcnt(0)
	v_mfma_f32_32x32x16_bf16 v[66:81], v[228:231], v[104:107], v[66:81]
	s_cmp_lt_u32 s3, s2
	s_cselect_b64 s[22:23], -1, 0
	s_cmp_ge_u32 s3, s2
	s_cbranch_scc1 .LBB0_97
	v_add_u32_e32 v242, 0x41, v178
	v_add_u32_e32 v246, 0x61, v178
	v_ashrrev_i32_e32 v243, 31, v242
	v_ashrrev_i32_e32 v247, 31, v246
	v_lshlrev_b64 v[140:141], 8, v[242:243]
	v_lshlrev_b64 v[142:143], 8, v[246:247]
	v_lshl_add_u64 v[242:243], v[170:171], 0, v[140:141]
	v_lshl_add_u64 v[246:247], v[170:171], 0, v[142:143]
	v_lshl_add_u64 v[140:141], v[176:177], 0, v[140:141]
	v_lshl_add_u64 v[144:145], v[176:177], 0, v[142:143]
	global_load_dwordx4 v[242:245], v[242:243], off
	s_nop 0
	global_load_dwordx4 v[246:249], v[246:247], off
	s_nop 0
	global_load_dwordx4 v[140:143], v[140:141], off
	s_nop 0
	global_load_dwordx4 v[144:147], v[144:145], off
	s_mov_b32 s100, 1
